# scan: static s_setprio 1 for the recurrence waves (0-3) for the duration of the scan phase
# baseline (speedup 1.0000x reference)
.LBB0_600:
	v_writelane_b32 v255, s88, 20
	s_nop 1
	v_writelane_b32 v255, s89, 21
	s_or_b64 exec, exec, s[6:7]
	s_waitcnt lgkmcnt(0)
	v_mov_b32_e32 v0, v254
	v_mov_b64_e32 v[2:3], s[58:59]
	s_barrier
	v_cmp_gt_u32_e32 vcc, 0x100, v254
	s_cbranch_vccz .Lprio_scan
	s_setprio 1
.Lprio_scan:
	flat_load_dwordx2 v[4:5], v[2:3] offset:192 sc0 sc1
	flat_load_dwordx2 v[6:7], v[2:3] offset:200 sc0 sc1
	flat_load_dwordx2 v[188:189], v[2:3] offset:208 sc0 sc1
	s_waitcnt vmcnt(0)
	s_add_u32 s66, s26, 0x13800000
	s_addc_u32 s67, s27, 0
	s_add_u32 s68, s26, 0x15900000
	s_addc_u32 s69, s27, 0
	s_add_u32 s64, s26, 0x2800000
	s_addc_u32 s65, s27, 0
	s_add_u32 s4, s26, 0x2dc00000
	s_addc_u32 s5, s27, 0
	v_writelane_b32 v255, s4, 22
	v_readfirstlane_b32 s0, v0
	s_waitcnt lgkmcnt(0)
	v_readfirstlane_b32 s71, v5
	v_writelane_b32 v255, s5, 23
	s_add_u32 s4, s26, 0x2b000000
	s_addc_u32 s5, s27, 0
	v_writelane_b32 v255, s4, 24
	v_readfirstlane_b32 s70, v4
	v_readfirstlane_b32 s73, v7
	v_writelane_b32 v255, s5, 25
	s_add_u32 s4, s26, 0x12a00000
	s_addc_u32 s5, s27, 0
	s_add_u32 s54, s26, 0x11200000
	v_writelane_b32 v255, s4, 26
	s_addc_u32 s55, s27, 0
	s_add_u32 s58, s26, 0x5c00000
	v_writelane_b32 v255, s5, 27
	s_addc_u32 s59, s27, 0
	v_readlane_b32 s4, v255, 7
	s_add_u32 s62, s26, 0x3000000
	v_readlane_b32 s5, v255, 8
	s_addc_u32 s63, s27, 0
	s_and_b64 vcc, exec, s[4:5]
	v_readfirstlane_b32 s72, v6
	s_cbranch_vccz .LBB0_732
	v_readlane_b32 s4, v255, 10
	v_readlane_b32 s5, v255, 11
	s_nop 1
	v_mov_b64_e32 v[2:3], s[4:5]
	flat_load_dwordx2 v[4:5], v[2:3] offset:80 sc0 sc1
	flat_load_dwordx2 v[6:7], v[2:3] offset:72 sc0 sc1
	flat_load_dwordx2 v[8:9], v[2:3] offset:64 sc0 sc1
	flat_load_dwordx2 v[10:11], v[2:3] offset:336 sc0 sc1
	flat_load_dwordx2 v[12:13], v[2:3] offset:232 sc0 sc1
	flat_load_dwordx2 v[14:15], v[2:3] offset:120 sc0 sc1
	s_waitcnt vmcnt(0) lgkmcnt(0)
	v_readfirstlane_b32 s76, v4
	v_readfirstlane_b32 s77, v5
	v_readfirstlane_b32 s78, v6
	v_readfirstlane_b32 s79, v7
	v_readfirstlane_b32 s80, v8
	v_readfirstlane_b32 s81, v9
	v_readfirstlane_b32 s82, v10
	v_readfirstlane_b32 s83, v11
	v_readfirstlane_b32 s84, v12
	v_readfirstlane_b32 s85, v13
	v_readfirstlane_b32 s6, v14
	v_readfirstlane_b32 s7, v15
	s_ashr_i32 s0, s0, 6
	v_and_b32_e32 v2, 15, v0
	v_bfe_u32 v131, v0, 4, 4
	s_add_i32 s23, s0, -4
	s_mulk_i32 s0, 0x2100
	v_lshlrev_b32_e32 v6, 3, v0
	v_lshlrev_b32_e32 v4, 8, v131
	v_lshlrev_b32_e32 v5, 4, v2
	s_add_i32 s0, s0, 0
	v_bfe_u32 v148, v0, 3, 3
	v_and_b32_e32 v6, 56, v6
	v_writelane_b32 v255, s6, 28
	s_movk_i32 s1, 0xff
	v_or_b32_e32 v136, 16, v131
	v_add3_u32 v141, 0, v4, v5
	v_and_b32_e32 v4, 0xf0, v0
	s_add_i32 s0, s0, 0x14c00
	v_mul_u32_u24_e32 v10, 0x84, v6
	v_lshlrev_b32_e32 v11, 2, v148
	v_writelane_b32 v255, s7, 29
	v_cmp_lt_i32_e64 s[6:7], s1, v0
	s_movk_i32 s1, 0x100
	v_lshlrev_b32_e32 v142, 2, v4
	v_lshlrev_b32_e32 v4, 8, v136
	v_add3_u32 v149, s0, v10, v11
	v_mov_b32_e32 v10, 5
	v_ashrrev_i32_e32 v99, 4, v0
	v_cmp_gt_i32_e64 s[8:9], s1, v0
	v_add3_u32 v145, 0, v4, v5
	v_and_b32_e32 v7, 7, v0
	v_bfe_u32 v147, v0, 5, 1
	v_and_b32_e32 v4, 31, v0
	v_lshlrev_b32_sdwa v153, v10, v0 dst_sel:DWORD dst_unused:UNUSED_PAD src0_sel:DWORD src1_sel:BYTE_0
	v_or_b32_sdwa v0, v0, s1 dst_sel:DWORD dst_unused:UNUSED_PAD src0_sel:BYTE_0 src1_sel:DWORD
	s_movk_i32 s4, 0x20ff
	v_lshrrev_b32_e32 v154, 4, v0
	v_lshlrev_b32_e32 v155, 5, v0
	v_mov_b32_e32 v0, 0xa040
	v_bitop3_b32 v140, v131, s4, 16 bitop3:0x36
	v_lshlrev_b32_e32 v3, 6, v131
	s_movk_i32 s4, 0xff40
	v_lshl_add_u32 v8, v4, 2, s0
	v_mul_u32_u24_e32 v9, 0x84, v147
	v_lshl_add_u32 v160, v99, 2, v0
	v_lshlrev_b32_e32 v0, 2, v7
	v_lshlrev_b32_e32 v98, 2, v2
	v_or_b32_e32 v137, 0x2000, v131
	v_xor_b32_e32 v138, 0x20ff, v131
	v_cmp_gt_u32_e64 s[10:11], 4, v2
	v_mov_b32_e32 v1, 0
	v_or_b32_e32 v139, 0x2010, v131
	s_mov_b32 s87, 0
	v_add3_u32 v143, 0, v142, v5
	v_lshlrev_b32_e32 v144, 6, v136
	v_mad_i32_i24 v146, v136, s4, v145
	v_or_b32_e32 v150, 8, v148
	v_or_b32_e32 v151, 16, v148
	v_or_b32_e32 v152, 24, v148
	v_or_b32_e32 v156, 0x1fe0, v131
	v_xor_b32_e32 v157, 31, v131
	v_or_b32_e32 v158, 0x1fe0, v154
	v_xor_b32_e32 v159, 31, v154
	v_or_b32_e32 v161, 0x100, v5
	v_lshl_or_b32 v162, v99, 5, v0
	s_mov_b32 s74, 0xf800000
	v_mov_b32_e32 v163, 0x260
	v_lshlrev_b32_e32 v100, 1, v2
	s_mov_b32 s75, 0xa800
	s_movk_i32 s40, 0x7fff
	s_mov_b32 s41, 0xac00
	s_movk_i32 s20, 0x15ff
	s_movk_i32 s21, 0x2bff
	s_movk_i32 s46, 0x41ff
	s_movk_i32 s47, 0x59ff
	s_movk_i32 s24, 0x61ff
	s_movk_i32 s44, 0x77ff
	s_mov_b32 s45, 0x8dff
	v_add_u32_e32 v164, v8, v9
	v_lshlrev_b32_e32 v102, 1, v6
	v_lshlrev_b32_e32 v104, 2, v4
	v_lshlrev_b32_e32 v165, 2, v3
	s_add_i32 s25, 0, 0x19000
	v_mov_b32_e32 v166, 7
	v_mov_b32_e32 v167, 0xa800
	s_mov_b32 s33, s2
	s_branch .LBB0_603
